# layer-1 MLP2 weight conversion: tiles 0..2303 done by workgroups 64.. at the end of the cmp2 phase (idle there); MLP1 tiles 0..2175 by workgroups 192.. in the cmp phase
# speedup vs baseline: 1.0065x; 1.0016x over previous
.LBB0_702:
	s_load_dwordx2 s[4:5], s[0:1], 0x88
	s_waitcnt lgkmcnt(0)
	v_writelane_b32 v232, s4, 25
	v_writelane_b32 v232, s5, 26
	v_mov_b32_e32 v0, v136
	s_and_b64 vcc, exec, s[10:11]
	s_cbranch_vccnz .LBB0_711
	s_load_dwordx2 s[4:5], s[0:1], 0x88
	v_ashrrev_i32_e32 v9, 3, v0
	v_lshlrev_b32_e32 v0, 3, v0
	v_and_b32_e32 v8, 56, v0
	v_lshl_add_u32 v2, v9, 2, 16
	s_waitcnt lgkmcnt(0)
	s_add_u32 s10, s4, 0x4000000
	s_addc_u32 s11, s5, 0
	s_movk_i32 s4, 0x104
	v_mul_u32_u24_e32 v3, 0x104, v8
	v_lshl_add_u32 v0, v8, 2, 16
	s_add_u32 s14, s52, 0x4800000
	v_mul_lo_u32 v1, v9, s4
	v_add_u32_e32 v17, v2, v3
	s_addc_u32 s15, s53, 0
	v_mov_b32_e32 v11, 0
	s_add_i32 s4, s2, 0x900
	s_lshl_b32 s4, s4, 6
	s_lshl_b32 s5, s34, 6
	s_movk_i32 s6, 0x800
	v_add_u32_e32 v16, v0, v1
	v_lshlrev_b32_e32 v10, 1, v8
	v_add_u32_e32 v18, 0x400, v17
	s_add_i32 s7, s2, 0x900
	s_branch .LBB0_705

.LBB0_1362:
	s_or_b64 exec, exec, s[16:17]
	s_cmp_lt_u32 s2, 64
	s_cbranch_scc1 .Lmv2_skip
	s_sub_i32 s60, s2, 64
	s_sub_i32 s61, s34, 64
	v_mov_b32_e32 v0, v136
	v_readlane_b32 s4, v232, 25
	v_readlane_b32 s5, v232, 26
	s_nop 3
	v_ashrrev_i32_e32 v9, 3, v0
	v_lshlrev_b32_e32 v0, 3, v0
	v_and_b32_e32 v8, 56, v0
	v_lshl_add_u32 v2, v9, 2, 16
	s_waitcnt lgkmcnt(0)
	s_add_u32 s10, s4, 0x4000000
	s_addc_u32 s11, s5, 0
	s_movk_i32 s4, 0x104
	v_mul_u32_u24_e32 v3, 0x104, v8
	v_lshl_add_u32 v0, v8, 2, 16
	s_add_u32 s14, s30, 0x4800000
	v_mul_lo_u32 v1, v9, s4
	v_add_u32_e32 v17, v2, v3
	s_addc_u32 s15, s31, 0
	v_mov_b32_e32 v11, 0
	s_lshl_b32 s4, s60, 6
	s_lshl_b32 s5, s61, 6
	s_movk_i32 s6, 0x800
	v_add_u32_e32 v16, v0, v1
	v_lshlrev_b32_e32 v10, 1, v8
	v_add_u32_e32 v18, 0x400, v17
	s_mov_b32 s7, s60
	s_branch .Lmv2_705
.Lmv2_704:
	s_or_b64 exec, exec, s[18:19]
	s_add_i32 s7, s7, s61
	s_add_i32 s4, s4, s5
	s_cmpk_lt_i32 s7, 0x900
	s_barrier
	s_cbranch_scc0 .Lmv2_done

.Lmv2_done:
.Lmv2_skip:
	s_waitcnt vmcnt(0)
	s_barrier
	s_and_saveexec_b64 s[10:11], s[90:91]
	s_cbranch_execz .LBB0_1414
	v_mov_b32_e32 v0, 0
	s_waitcnt vmcnt(0) expcnt(0) lgkmcnt(0)
	ds_read_b32 v2, v0
	ds_read_b32 v1, v0 offset:4
	s_waitcnt lgkmcnt(1)
	v_cmp_ne_u32_e32 vcc, 0, v2
	s_cbranch_vccnz .LBB0_1378
	s_add_u32 s12, s30, 0x24400200
	s_addc_u32 s13, s31, 0
	s_add_u32 s14, s30, 0x24400400
	s_addc_u32 s15, s31, 0
	s_add_u32 s16, s30, 0x24400500
	s_addc_u32 s17, s31, 0
	s_add_u32 s18, s30, 0x24400600
	s_addc_u32 s19, s31, 0
	s_add_u32 s20, s30, 0x24400700
	s_addc_u32 s21, s31, 0
	s_add_u32 s22, s30, 0x24400800
	s_addc_u32 s23, s31, 0
	s_add_u32 s56, s30, 0x24400900
	s_addc_u32 s57, s31, 0
	s_add_u32 s58, s30, 0x24400a00
	s_addc_u32 s59, s31, 0
	s_add_u32 s60, s30, 0x24400b00
	s_addc_u32 s61, s31, 0
	s_add_u32 s62, s30, 0x24400c00
	s_addc_u32 s63, s31, 0
	s_add_u32 s64, s30, 0x24400d00
	s_addc_u32 s65, s31, 0
	s_add_u32 s66, s30, 0x24400e00
	s_addc_u32 s67, s31, 0
	s_add_u32 s68, s30, 0x24400f00
	v_readlane_b32 s0, v232, 5
	s_addc_u32 s69, s31, 0
	v_readlane_b32 s1, v232, 6
	s_add_u32 s70, s30, 0x24401000
	s_load_dword s4, s[0:1], 0x108
	s_addc_u32 s71, s31, 0
	s_add_u32 s72, s30, 0x24401100
	s_addc_u32 s73, s31, 0
	s_add_u32 s74, s30, 0x24401200
	s_addc_u32 s75, s31, 0
	s_waitcnt lgkmcnt(0)
	s_mul_i32 s4, s35, s4
	s_add_u32 s76, s30, 0x24401300
	s_mul_i32 s4, s4, s34
	s_addc_u32 s77, s31, 0
	s_mov_b32 s5, 1
	s_branch .LBB0_1366
